# up epilogue H stores with default (write-back) cache policy instead of nt, on top of the K-loop edits
# baseline (speedup 1.0000x reference)
; __device__ __forceinline__ unsigned cvt_pk_bf16(float lo, float hi) { unsigned r; asm volatile("v_cvt_pk_bf16_f32 %0, %1, %2" : "=v"(r) : "v"(lo), "v"(hi)); return r; }
;     __device__ __forceinline__ void operator()(const f32x4 (&acc)[2][2][4][2], const Unit& u, int ui, int wr, int wc, int fr, int fq) const {
;     ...
;         const int row0 = u.pm * BM + wr * 64 + fr, col0 = u.pn * HALF + wc * 32 + 8 * fq;
;         float rs[2][4];
; #pragma unroll
;         for (int ai = 0; ai < 2; ++ai)
; #pragma unroll
;             for (int m = 0; m < 4; ++m) rs[ai][m] = row_rstd(lds, ui, ai * HALF + wr * 64 + m * 16 + fr);
; #pragma unroll
;         for (int ai = 0; ai < 2; ++ai)
; #pragma unroll
;             for (int m = 0; m < 4; ++m) { const float r = rs[ai][m]; const int row = row0 + ai * HALF + m * 16;
;                 const float c1 = r * -1.44269504089f, r2 = r * r; u32x4 w;
; #pragma unroll
;                 for (int n = 0; n < 2; ++n)
; #pragma unroll
;                     for (int p = 0; p < 2; ++p) { const f32x2 g = (f32x2){acc[ai][0][m][n][2 * p], acc[ai][0][m][n][2 * p + 1]}, uu = (f32x2){acc[ai][1][m][n][2 * p], acc[ai][1][m][n][2 * p + 1]};
;                         const f32x2 t = g * c1; f32x2 d; d.x = __builtin_amdgcn_exp2f(t.x); d.y = __builtin_amdgcn_exp2f(t.y); d = d + 1.0f;
;                         f32x2 q; q.x = __builtin_amdgcn_rcpf(d.x); q.y = __builtin_amdgcn_rcpf(d.y);
;                         const f32x2 hh = (g * uu) * (q * r2); w[2 * n + p] = cvt_pk_bf16(hh.x, hh.y); }
;                 __builtin_nontemporal_store(w, (u32x4*)(H + (size_t)row * ldh + col0)); }
.LBB0_449:
	v_mov_b32_e32 v140, v147
	v_mov_b32_e32 v167, v164
	v_pk_mul_f32 v[120:121], v[124:125], v[120:121]
	v_add_u32_e32 v171, s35, v140
	v_lshlrev_b32_e32 v140, 2, v171
	v_lshl_add_u32 v140, s48, 10, v140
	v_add_u32_e32 v140, 0x20400, v140
	ds_read2_b32 v[168:169], v140 offset1:16
	ds_read2_b32 v[162:163], v140 offset0:32 offset1:48
	ds_read2_b32 v[142:143], v140 offset0:128 offset1:144
	ds_read2_b32 v[140:141], v140 offset0:160 offset1:176
	v_pk_mul_f32 v[122:123], v[126:127], v[122:123]
	s_waitcnt lgkmcnt(0)
	v_mul_f32_e32 v172, 0xbfb8aa3b, v168
	v_pk_mul_f32 v[174:175], v[124:125], v[172:173] op_sel_hi:[1,0]
	v_pk_mul_f32 v[124:125], v[126:127], v[172:173] op_sel_hi:[1,0]
	v_exp_f32_e32 v174, v174
	v_exp_f32_e32 v175, v175
	v_exp_f32_e32 v124, v124
	v_exp_f32_e32 v125, v125
	v_mul_f32_e32 v168, v168, v168
	v_pk_add_f32 v[174:175], v[174:175], 1.0 op_sel_hi:[1,0]
	v_pk_mul_f32 v[112:113], v[116:117], v[112:113]
	v_rcp_f32_e32 v174, v174
	v_rcp_f32_e32 v175, v175
	v_pk_add_f32 v[124:125], v[124:125], 1.0 op_sel_hi:[1,0]
	v_pk_mul_f32 v[114:115], v[118:119], v[114:115]
	v_rcp_f32_e32 v124, v124
	v_rcp_f32_e32 v125, v125
	v_pk_mul_f32 v[126:127], v[168:169], v[174:175] op_sel_hi:[0,1]
	v_pk_mul_f32 v[120:121], v[120:121], v[126:127]
	v_pk_mul_f32 v[126:127], v[116:117], v[172:173] op_sel_hi:[1,0]
	v_pk_mul_f32 v[124:125], v[168:169], v[124:125] op_sel_hi:[0,1]
	v_exp_f32_e32 v126, v126
	v_exp_f32_e32 v127, v127
	v_pk_mul_f32 v[122:123], v[122:123], v[124:125]
	v_pk_mul_f32 v[124:125], v[118:119], v[172:173] op_sel_hi:[1,0]
	v_cvt_pk_bf16_f32 v120, v120, v121
	v_cvt_pk_bf16_f32 v121, v122, v123
	v_pk_add_f32 v[122:123], v[126:127], 1.0 op_sel_hi:[1,0]
	v_exp_f32_e32 v124, v124
	v_exp_f32_e32 v125, v125
	v_rcp_f32_e32 v122, v122
	v_rcp_f32_e32 v123, v123
	s_lshl_b32 s5, s47, 7
	v_pk_add_f32 v[116:117], v[124:125], 1.0 op_sel_hi:[1,0]
	s_or_b32 s5, s5, s36
	v_rcp_f32_e32 v116, v116
	v_rcp_f32_e32 v117, v117
	v_pk_mul_f32 v[118:119], v[168:169], v[122:123] op_sel_hi:[0,1]
	v_pk_mul_f32 v[112:113], v[112:113], v[118:119]
	v_mul_f32_e32 v118, 0xbfb8aa3b, v169
	v_cvt_pk_bf16_f32 v122, v112, v113
	v_pk_mul_f32 v[112:113], v[168:169], v[116:117] op_sel_hi:[0,1]
	v_pk_mul_f32 v[124:125], v[108:109], v[118:119] op_sel_hi:[1,0]
	v_lshl_add_u32 v170, v167, 3, s5
	v_pk_mul_f32 v[112:113], v[114:115], v[112:113]
	v_exp_f32_e32 v124, v124
	v_exp_f32_e32 v125, v125
	v_lshl_add_u32 v167, s46, 8, v171
	v_ashrrev_i32_e32 v171, 31, v170
	v_cvt_pk_bf16_f32 v123, v112, v113
	v_mov_b64_e32 v[112:113], s[20:21]
	v_pk_mul_f32 v[104:105], v[108:109], v[104:105]
	v_pk_mul_f32 v[108:109], v[110:111], v[118:119] op_sel_hi:[1,0]
	v_mad_i64_i32 v[116:117], s[14:15], v167, s59, v[112:113]
	v_lshlrev_b64 v[114:115], 1, v[170:171]
	v_exp_f32_e32 v108, v108
	v_exp_f32_e32 v109, v109
	v_lshl_add_u64 v[116:117], v[116:117], 0, v[114:115]
	global_store_dwordx4 v[116:117], v[120:123], off
	v_mul_f32_e32 v116, v169, v169
	v_pk_add_f32 v[108:109], v[108:109], 1.0 op_sel_hi:[1,0]
	v_pk_add_f32 v[120:121], v[124:125], 1.0 op_sel_hi:[1,0]
	v_rcp_f32_e32 v108, v108
	v_rcp_f32_e32 v120, v120
	v_rcp_f32_e32 v121, v121
	v_rcp_f32_e32 v109, v109
	v_pk_mul_f32 v[106:107], v[110:111], v[106:107]
	v_pk_mul_f32 v[96:97], v[100:101], v[96:97]
	v_pk_mul_f32 v[110:111], v[116:117], v[120:121] op_sel_hi:[0,1]
	v_pk_mul_f32 v[104:105], v[104:105], v[110:111]
	v_pk_mul_f32 v[110:111], v[100:101], v[118:119] op_sel_hi:[1,0]
	v_pk_mul_f32 v[108:109], v[116:117], v[108:109] op_sel_hi:[0,1]
	v_exp_f32_e32 v110, v110
	v_exp_f32_e32 v111, v111
	v_pk_mul_f32 v[106:107], v[106:107], v[108:109]
	v_pk_mul_f32 v[108:109], v[102:103], v[118:119] op_sel_hi:[1,0]
	v_cvt_pk_bf16_f32 v104, v104, v105
	v_cvt_pk_bf16_f32 v105, v106, v107
	v_pk_add_f32 v[106:107], v[110:111], 1.0 op_sel_hi:[1,0]
	v_exp_f32_e32 v108, v108
	v_exp_f32_e32 v109, v109
	v_rcp_f32_e32 v106, v106
	v_rcp_f32_e32 v107, v107
	v_pk_mul_f32 v[98:99], v[102:103], v[98:99]
	v_pk_add_f32 v[100:101], v[108:109], 1.0 op_sel_hi:[1,0]
	v_pk_mul_f32 v[88:89], v[92:93], v[88:89]
	v_rcp_f32_e32 v100, v100
	v_rcp_f32_e32 v101, v101
	v_pk_mul_f32 v[102:103], v[116:117], v[106:107] op_sel_hi:[0,1]
	v_pk_mul_f32 v[96:97], v[96:97], v[102:103]
	v_pk_mul_f32 v[90:91], v[94:95], v[90:91]
	v_cvt_pk_bf16_f32 v106, v96, v97
	v_pk_mul_f32 v[96:97], v[116:117], v[100:101] op_sel_hi:[0,1]
	v_pk_mul_f32 v[96:97], v[98:99], v[96:97]
	v_mul_f32_e32 v98, 0xbfb8aa3b, v162
	v_pk_mul_f32 v[100:101], v[92:93], v[98:99] op_sel_hi:[1,0]
	v_pk_mul_f32 v[92:93], v[94:95], v[98:99] op_sel_hi:[1,0]
	v_exp_f32_e32 v100, v100
	v_exp_f32_e32 v101, v101
	v_exp_f32_e32 v92, v92
	v_exp_f32_e32 v93, v93
	v_cvt_pk_bf16_f32 v107, v96, v97
	v_pk_add_f32 v[100:101], v[100:101], 1.0 op_sel_hi:[1,0]
	v_add_u32_e32 v96, 16, v167
	v_rcp_f32_e32 v100, v100
	v_rcp_f32_e32 v101, v101
	v_mad_i64_i32 v[96:97], s[14:15], v96, s59, v[112:113]
	v_pk_add_f32 v[92:93], v[92:93], 1.0 op_sel_hi:[1,0]
	v_lshl_add_u64 v[96:97], v[96:97], 0, v[114:115]
	v_rcp_f32_e32 v92, v92
	v_rcp_f32_e32 v93, v93
	global_store_dwordx4 v[96:97], v[104:107], off
	v_mul_f32_e32 v96, v162, v162
	v_pk_mul_f32 v[94:95], v[96:97], v[100:101] op_sel_hi:[0,1]
	v_pk_mul_f32 v[88:89], v[88:89], v[94:95]
	v_pk_mul_f32 v[94:95], v[84:85], v[98:99] op_sel_hi:[1,0]
	v_pk_mul_f32 v[92:93], v[96:97], v[92:93] op_sel_hi:[0,1]
	v_exp_f32_e32 v94, v94
	v_exp_f32_e32 v95, v95
	v_pk_mul_f32 v[90:91], v[90:91], v[92:93]
	v_pk_mul_f32 v[92:93], v[86:87], v[98:99] op_sel_hi:[1,0]
	v_cvt_pk_bf16_f32 v88, v88, v89
	v_cvt_pk_bf16_f32 v89, v90, v91
	v_pk_add_f32 v[90:91], v[94:95], 1.0 op_sel_hi:[1,0]
	v_exp_f32_e32 v92, v92
	v_exp_f32_e32 v93, v93
; __device__ __forceinline__ unsigned cvt_pk_bf16(float lo, float hi) { unsigned r; asm volatile("v_cvt_pk_bf16_f32 %0, %1, %2" : "=v"(r) : "v"(lo), "v"(hi)); return r; }
;     __device__ __forceinline__ void operator()(const f32x4 (&acc)[2][2][4][2], const Unit& u, int ui, int wr, int wc, int fr, int fq) const {
;     ...
;             for (int m = 0; m < 4; ++m) { const float r = rs[ai][m]; const int row = row0 + ai * HALF + m * 16;
;                 const float c1 = r * -1.44269504089f, r2 = r * r; u32x4 w;
; #pragma unroll
;                 for (int n = 0; n < 2; ++n)
; #pragma unroll
;                     for (int p = 0; p < 2; ++p) { const f32x2 g = (f32x2){acc[ai][0][m][n][2 * p], acc[ai][0][m][n][2 * p + 1]}, uu = (f32x2){acc[ai][1][m][n][2 * p], acc[ai][1][m][n][2 * p + 1]};
;                         const f32x2 t = g * c1; f32x2 d; d.x = __builtin_amdgcn_exp2f(t.x); d.y = __builtin_amdgcn_exp2f(t.y); d = d + 1.0f;
;                         f32x2 q; q.x = __builtin_amdgcn_rcpf(d.x); q.y = __builtin_amdgcn_rcpf(d.y);
;                         const f32x2 hh = (g * uu) * (q * r2); w[2 * n + p] = cvt_pk_bf16(hh.x, hh.y); }
;                 __builtin_nontemporal_store(w, (u32x4*)(H + (size_t)row * ldh + col0)); }
	v_rcp_f32_e32 v90, v90
	v_rcp_f32_e32 v91, v91
	v_pk_mul_f32 v[80:81], v[84:85], v[80:81]
	v_pk_add_f32 v[84:85], v[92:93], 1.0 op_sel_hi:[1,0]
	v_pk_mul_f32 v[82:83], v[86:87], v[82:83]
	v_rcp_f32_e32 v84, v84
	v_rcp_f32_e32 v85, v85
	v_pk_mul_f32 v[86:87], v[96:97], v[90:91] op_sel_hi:[0,1]
	v_pk_mul_f32 v[80:81], v[80:81], v[86:87]
	v_pk_mul_f32 v[72:73], v[76:77], v[72:73]
	v_cvt_pk_bf16_f32 v90, v80, v81
	v_pk_mul_f32 v[80:81], v[96:97], v[84:85] op_sel_hi:[0,1]
	v_pk_mul_f32 v[80:81], v[82:83], v[80:81]
	v_mul_f32_e32 v82, 0xbfb8aa3b, v163
	v_pk_mul_f32 v[84:85], v[76:77], v[82:83] op_sel_hi:[1,0]
	v_pk_mul_f32 v[76:77], v[78:79], v[82:83] op_sel_hi:[1,0]
	v_exp_f32_e32 v84, v84
	v_exp_f32_e32 v85, v85
	v_exp_f32_e32 v76, v76
	v_exp_f32_e32 v77, v77
	v_cvt_pk_bf16_f32 v91, v80, v81
	v_pk_add_f32 v[84:85], v[84:85], 1.0 op_sel_hi:[1,0]
	v_add_u32_e32 v80, 32, v167
	v_rcp_f32_e32 v84, v84
	v_rcp_f32_e32 v85, v85
	v_mad_i64_i32 v[80:81], s[14:15], v80, s59, v[112:113]
	v_pk_add_f32 v[76:77], v[76:77], 1.0 op_sel_hi:[1,0]
	v_lshl_add_u64 v[80:81], v[80:81], 0, v[114:115]
	v_rcp_f32_e32 v76, v76
	v_rcp_f32_e32 v77, v77
	global_store_dwordx4 v[80:81], v[88:91], off
	v_mul_f32_e32 v80, v163, v163
	v_pk_mul_f32 v[74:75], v[78:79], v[74:75]
	v_pk_mul_f32 v[78:79], v[80:81], v[84:85] op_sel_hi:[0,1]
	v_pk_mul_f32 v[72:73], v[72:73], v[78:79]
	v_pk_mul_f32 v[78:79], v[68:69], v[82:83] op_sel_hi:[1,0]
	v_pk_mul_f32 v[76:77], v[80:81], v[76:77] op_sel_hi:[0,1]
	v_exp_f32_e32 v78, v78
	v_exp_f32_e32 v79, v79
	v_pk_mul_f32 v[74:75], v[74:75], v[76:77]
	v_pk_mul_f32 v[76:77], v[70:71], v[82:83] op_sel_hi:[1,0]
	v_cvt_pk_bf16_f32 v72, v72, v73
	v_cvt_pk_bf16_f32 v73, v74, v75
	v_pk_add_f32 v[74:75], v[78:79], 1.0 op_sel_hi:[1,0]
	v_exp_f32_e32 v76, v76
	v_exp_f32_e32 v77, v77
	v_rcp_f32_e32 v74, v74
	v_rcp_f32_e32 v75, v75
	v_pk_mul_f32 v[64:65], v[68:69], v[64:65]
	v_pk_add_f32 v[68:69], v[76:77], 1.0 op_sel_hi:[1,0]
	v_pk_mul_f32 v[66:67], v[70:71], v[66:67]
	v_rcp_f32_e32 v68, v68
	v_rcp_f32_e32 v69, v69
	v_pk_mul_f32 v[70:71], v[80:81], v[74:75] op_sel_hi:[0,1]
	v_pk_mul_f32 v[64:65], v[64:65], v[70:71]
	v_pk_mul_f32 v[56:57], v[60:61], v[56:57]
	v_cvt_pk_bf16_f32 v74, v64, v65
	v_pk_mul_f32 v[64:65], v[80:81], v[68:69] op_sel_hi:[0,1]
	v_pk_mul_f32 v[64:65], v[66:67], v[64:65]
	v_mul_f32_e32 v66, 0xbfb8aa3b, v142
	v_pk_mul_f32 v[68:69], v[60:61], v[66:67] op_sel_hi:[1,0]
	v_pk_mul_f32 v[60:61], v[62:63], v[66:67] op_sel_hi:[1,0]
	v_exp_f32_e32 v68, v68
	v_exp_f32_e32 v69, v69
	v_exp_f32_e32 v60, v60
	v_exp_f32_e32 v61, v61
	v_cvt_pk_bf16_f32 v75, v64, v65
	v_pk_add_f32 v[68:69], v[68:69], 1.0 op_sel_hi:[1,0]
	v_add_u32_e32 v64, 48, v167
	v_rcp_f32_e32 v68, v68
	v_rcp_f32_e32 v69, v69
	v_mad_i64_i32 v[64:65], s[14:15], v64, s59, v[112:113]
	v_pk_add_f32 v[60:61], v[60:61], 1.0 op_sel_hi:[1,0]
	v_lshl_add_u64 v[64:65], v[64:65], 0, v[114:115]
	v_rcp_f32_e32 v60, v60
	v_rcp_f32_e32 v61, v61
	global_store_dwordx4 v[64:65], v[72:75], off
	v_add_u32_e32 v65, 0x80, v167
	v_mul_f32_e32 v64, v142, v142
	v_pk_mul_f32 v[58:59], v[62:63], v[58:59]
	v_pk_mul_f32 v[62:63], v[64:65], v[68:69] op_sel_hi:[0,1]
	v_pk_mul_f32 v[56:57], v[56:57], v[62:63]
	v_pk_mul_f32 v[62:63], v[52:53], v[66:67] op_sel_hi:[1,0]
	v_pk_mul_f32 v[60:61], v[64:65], v[60:61] op_sel_hi:[0,1]
	v_exp_f32_e32 v62, v62
	v_exp_f32_e32 v63, v63
	v_pk_mul_f32 v[58:59], v[58:59], v[60:61]
	v_pk_mul_f32 v[60:61], v[54:55], v[66:67] op_sel_hi:[1,0]
	v_cvt_pk_bf16_f32 v56, v56, v57
	v_cvt_pk_bf16_f32 v57, v58, v59
	v_pk_add_f32 v[58:59], v[62:63], 1.0 op_sel_hi:[1,0]
	v_exp_f32_e32 v60, v60
	v_exp_f32_e32 v61, v61
	v_rcp_f32_e32 v58, v58
	v_rcp_f32_e32 v59, v59
	v_pk_mul_f32 v[48:49], v[52:53], v[48:49]
	v_pk_add_f32 v[52:53], v[60:61], 1.0 op_sel_hi:[1,0]
	v_pk_mul_f32 v[50:51], v[54:55], v[50:51]
	v_rcp_f32_e32 v52, v52
	v_rcp_f32_e32 v53, v53
	v_pk_mul_f32 v[54:55], v[64:65], v[58:59] op_sel_hi:[0,1]
	v_pk_mul_f32 v[48:49], v[48:49], v[54:55]
	v_pk_mul_f32 v[40:41], v[44:45], v[40:41]
	v_cvt_pk_bf16_f32 v58, v48, v49
	v_pk_mul_f32 v[48:49], v[64:65], v[52:53] op_sel_hi:[0,1]
	v_pk_mul_f32 v[48:49], v[50:51], v[48:49]
	v_mul_f32_e32 v50, 0xbfb8aa3b, v143
	v_pk_mul_f32 v[52:53], v[44:45], v[50:51] op_sel_hi:[1,0]
	v_pk_mul_f32 v[44:45], v[46:47], v[50:51] op_sel_hi:[1,0]
	v_exp_f32_e32 v52, v52
	v_exp_f32_e32 v53, v53
	v_exp_f32_e32 v44, v44
	v_exp_f32_e32 v45, v45
	v_cvt_pk_bf16_f32 v59, v48, v49
	v_pk_add_f32 v[52:53], v[52:53], 1.0 op_sel_hi:[1,0]
	v_mad_i64_i32 v[48:49], s[14:15], v65, s59, v[112:113]
	v_rcp_f32_e32 v52, v52
	v_rcp_f32_e32 v53, v53
	v_pk_add_f32 v[44:45], v[44:45], 1.0 op_sel_hi:[1,0]
	v_lshl_add_u64 v[48:49], v[48:49], 0, v[114:115]
	v_rcp_f32_e32 v44, v44
	v_rcp_f32_e32 v45, v45
	global_store_dwordx4 v[48:49], v[56:59], off
	v_mul_f32_e32 v48, v143, v143
	v_pk_mul_f32 v[42:43], v[46:47], v[42:43]
	v_pk_mul_f32 v[46:47], v[48:49], v[52:53] op_sel_hi:[0,1]
; __device__ __forceinline__ unsigned cvt_pk_bf16(float lo, float hi) { unsigned r; asm volatile("v_cvt_pk_bf16_f32 %0, %1, %2" : "=v"(r) : "v"(lo), "v"(hi)); return r; }
;     __device__ __forceinline__ void operator()(const f32x4 (&acc)[2][2][4][2], const Unit& u, int ui, int wr, int wc, int fr, int fq) const {
;     ...
;             for (int m = 0; m < 4; ++m) { const float r = rs[ai][m]; const int row = row0 + ai * HALF + m * 16;
;                 const float c1 = r * -1.44269504089f, r2 = r * r; u32x4 w;
; #pragma unroll
;                 for (int n = 0; n < 2; ++n)
; #pragma unroll
;                     for (int p = 0; p < 2; ++p) { const f32x2 g = (f32x2){acc[ai][0][m][n][2 * p], acc[ai][0][m][n][2 * p + 1]}, uu = (f32x2){acc[ai][1][m][n][2 * p], acc[ai][1][m][n][2 * p + 1]};
;                         const f32x2 t = g * c1; f32x2 d; d.x = __builtin_amdgcn_exp2f(t.x); d.y = __builtin_amdgcn_exp2f(t.y); d = d + 1.0f;
;                         f32x2 q; q.x = __builtin_amdgcn_rcpf(d.x); q.y = __builtin_amdgcn_rcpf(d.y);
;                         const f32x2 hh = (g * uu) * (q * r2); w[2 * n + p] = cvt_pk_bf16(hh.x, hh.y); }
;                 __builtin_nontemporal_store(w, (u32x4*)(H + (size_t)row * ldh + col0)); }
	v_pk_mul_f32 v[40:41], v[40:41], v[46:47]
	v_pk_mul_f32 v[46:47], v[36:37], v[50:51] op_sel_hi:[1,0]
	v_pk_mul_f32 v[44:45], v[48:49], v[44:45] op_sel_hi:[0,1]
	v_exp_f32_e32 v46, v46
	v_exp_f32_e32 v47, v47
	v_pk_mul_f32 v[42:43], v[42:43], v[44:45]
	v_pk_mul_f32 v[44:45], v[38:39], v[50:51] op_sel_hi:[1,0]
	v_cvt_pk_bf16_f32 v40, v40, v41
	v_cvt_pk_bf16_f32 v41, v42, v43
	v_pk_add_f32 v[42:43], v[46:47], 1.0 op_sel_hi:[1,0]
	v_exp_f32_e32 v44, v44
	v_exp_f32_e32 v45, v45
	v_rcp_f32_e32 v42, v42
	v_rcp_f32_e32 v43, v43
	v_pk_mul_f32 v[32:33], v[36:37], v[32:33]
	v_pk_add_f32 v[36:37], v[44:45], 1.0 op_sel_hi:[1,0]
	v_pk_mul_f32 v[34:35], v[38:39], v[34:35]
	v_rcp_f32_e32 v36, v36
	v_rcp_f32_e32 v37, v37
	v_pk_mul_f32 v[38:39], v[48:49], v[42:43] op_sel_hi:[0,1]
	v_pk_mul_f32 v[32:33], v[32:33], v[38:39]
	v_pk_mul_f32 v[24:25], v[28:29], v[24:25]
	v_cvt_pk_bf16_f32 v42, v32, v33
	v_pk_mul_f32 v[32:33], v[48:49], v[36:37] op_sel_hi:[0,1]
	v_pk_mul_f32 v[32:33], v[34:35], v[32:33]
	v_mul_f32_e32 v34, 0xbfb8aa3b, v140
	v_pk_mul_f32 v[36:37], v[28:29], v[34:35] op_sel_hi:[1,0]
	v_pk_mul_f32 v[28:29], v[30:31], v[34:35] op_sel_hi:[1,0]
	v_exp_f32_e32 v36, v36
	v_exp_f32_e32 v37, v37
	v_exp_f32_e32 v28, v28
	v_exp_f32_e32 v29, v29
	v_cvt_pk_bf16_f32 v43, v32, v33
	v_pk_add_f32 v[36:37], v[36:37], 1.0 op_sel_hi:[1,0]
	v_add_u32_e32 v32, 0x90, v167
	v_rcp_f32_e32 v36, v36
	v_rcp_f32_e32 v37, v37
	v_mad_i64_i32 v[32:33], s[14:15], v32, s59, v[112:113]
	v_pk_add_f32 v[28:29], v[28:29], 1.0 op_sel_hi:[1,0]
	v_lshl_add_u64 v[32:33], v[32:33], 0, v[114:115]
	v_rcp_f32_e32 v28, v28
	v_rcp_f32_e32 v29, v29
	global_store_dwordx4 v[32:33], v[40:43], off
	v_mul_f32_e32 v32, v140, v140
	v_pk_mul_f32 v[26:27], v[30:31], v[26:27]
	v_pk_mul_f32 v[30:31], v[32:33], v[36:37] op_sel_hi:[0,1]
	v_pk_mul_f32 v[24:25], v[24:25], v[30:31]
	v_pk_mul_f32 v[30:31], v[20:21], v[34:35] op_sel_hi:[1,0]
	v_pk_mul_f32 v[28:29], v[32:33], v[28:29] op_sel_hi:[0,1]
	v_exp_f32_e32 v30, v30
	v_exp_f32_e32 v31, v31
	v_pk_mul_f32 v[26:27], v[26:27], v[28:29]
	v_pk_mul_f32 v[28:29], v[22:23], v[34:35] op_sel_hi:[1,0]
	v_cvt_pk_bf16_f32 v24, v24, v25
	v_cvt_pk_bf16_f32 v25, v26, v27
	v_pk_add_f32 v[26:27], v[30:31], 1.0 op_sel_hi:[1,0]
	v_exp_f32_e32 v28, v28
	v_exp_f32_e32 v29, v29
	v_rcp_f32_e32 v26, v26
	v_rcp_f32_e32 v27, v27
	v_pk_mul_f32 v[16:17], v[20:21], v[16:17]
	v_pk_add_f32 v[20:21], v[28:29], 1.0 op_sel_hi:[1,0]
	v_pk_mul_f32 v[18:19], v[22:23], v[18:19]
	v_rcp_f32_e32 v20, v20
	v_rcp_f32_e32 v21, v21
	v_pk_mul_f32 v[22:23], v[32:33], v[26:27] op_sel_hi:[0,1]
	v_pk_mul_f32 v[16:17], v[16:17], v[22:23]
	v_pk_mul_f32 v[8:9], v[12:13], v[8:9]
	v_cvt_pk_bf16_f32 v26, v16, v17
	v_pk_mul_f32 v[16:17], v[32:33], v[20:21] op_sel_hi:[0,1]
	v_pk_mul_f32 v[16:17], v[18:19], v[16:17]
	v_mul_f32_e32 v18, 0xbfb8aa3b, v141
	v_pk_mul_f32 v[20:21], v[12:13], v[18:19] op_sel_hi:[1,0]
	v_pk_mul_f32 v[12:13], v[14:15], v[18:19] op_sel_hi:[1,0]
	v_exp_f32_e32 v20, v20
	v_exp_f32_e32 v21, v21
	v_exp_f32_e32 v12, v12
	v_exp_f32_e32 v13, v13
	v_cvt_pk_bf16_f32 v27, v16, v17
	v_pk_add_f32 v[20:21], v[20:21], 1.0 op_sel_hi:[1,0]
	v_add_u32_e32 v16, 0xa0, v167
	v_rcp_f32_e32 v20, v20
	v_rcp_f32_e32 v21, v21
	v_mad_i64_i32 v[16:17], s[14:15], v16, s59, v[112:113]
	v_pk_add_f32 v[12:13], v[12:13], 1.0 op_sel_hi:[1,0]
	v_lshl_add_u64 v[16:17], v[16:17], 0, v[114:115]
	v_rcp_f32_e32 v12, v12
	v_rcp_f32_e32 v13, v13
	global_store_dwordx4 v[16:17], v[24:27], off
	v_mul_f32_e32 v16, v141, v141
	v_pk_mul_f32 v[10:11], v[14:15], v[10:11]
	v_pk_mul_f32 v[14:15], v[16:17], v[20:21] op_sel_hi:[0,1]
	v_pk_mul_f32 v[8:9], v[8:9], v[14:15]
	v_pk_mul_f32 v[14:15], v[4:5], v[18:19] op_sel_hi:[1,0]
	v_pk_mul_f32 v[12:13], v[16:17], v[12:13] op_sel_hi:[0,1]
	v_exp_f32_e32 v14, v14
	v_exp_f32_e32 v15, v15
	v_pk_mul_f32 v[10:11], v[10:11], v[12:13]
	v_pk_mul_f32 v[12:13], v[6:7], v[18:19] op_sel_hi:[1,0]
	v_cvt_pk_bf16_f32 v8, v8, v9
	v_cvt_pk_bf16_f32 v9, v10, v11
	v_pk_add_f32 v[10:11], v[14:15], 1.0 op_sel_hi:[1,0]
	v_exp_f32_e32 v12, v12
	v_exp_f32_e32 v13, v13
	v_rcp_f32_e32 v10, v10
	v_rcp_f32_e32 v11, v11
	v_pk_mul_f32 v[0:1], v[4:5], v[0:1]
	v_pk_add_f32 v[4:5], v[12:13], 1.0 op_sel_hi:[1,0]
	v_pk_mul_f32 v[2:3], v[6:7], v[2:3]
	v_rcp_f32_e32 v4, v4
	v_rcp_f32_e32 v5, v5
	v_pk_mul_f32 v[6:7], v[16:17], v[10:11] op_sel_hi:[0,1]
	v_pk_mul_f32 v[0:1], v[0:1], v[6:7]
	s_andn2_b64 vcc, exec, s[8:9]
	v_cvt_pk_bf16_f32 v10, v0, v1
	v_pk_mul_f32 v[0:1], v[16:17], v[4:5] op_sel_hi:[0,1]
	v_pk_mul_f32 v[0:1], v[2:3], v[0:1]
	s_mov_b64 s[8:9], -1
	v_cvt_pk_bf16_f32 v11, v0, v1
	v_add_u32_e32 v0, 0xb0, v167
	v_mad_i64_i32 v[0:1], s[14:15], v0, s59, v[112:113]
	v_lshl_add_u64 v[0:1], v[0:1], 0, v[114:115]
	global_store_dwordx4 v[0:1], v[8:11], off
	s_cbranch_vccnz .LBB0_442
	s_andn2_b64 vcc, exec, s[0:1]
	s_cbranch_vccnz .LBB0_441
	s_barrier
	s_branch .LBB0_441
